# p0_rows: four quarter-row loads issued together with counted waits; ml_out gate block: MLM/MLDN loads issued before the lane scans
# baseline (speedup 1.0000x reference)
; __device__ __forceinline__ float logsig(float x) { return fminf(x, 0.f) - __logf(1.f + __expf(-fabsf(x))); }
; __device__ __forceinline__ void ml_out(LAS unsigned char* L, const bf16_t* Z, const float* GATES, const bf16_t* MLC, const float* MLDN, const float* MLM, const float* gain, bf16_t* Y) {
;     ...
;             if (wid == 0) { const int t = g ? (64 * c + 63 - lane) : (64 * c + lane); const size_t row = (size_t)b * S_ + t;
;                 const float fpre = GATES[row * 16 + g * 8 + 4 + h], ipre = GATES[row * 16 + g * 8 + h];
;                 float bc = logsig(fpre);
;                 for (int o = 1; o < 64; o <<= 1) { const float v = __shfl_up(bc, o); if (lane >= o) bc += v; }
;                 const float e = ipre - bc; float cm = e;
;                 for (int o = 1; o < 64; o <<= 1) { const float v = __shfl_up(cm, o); if (lane >= o) cm = fmaxf(cm, v); }
;                 const float m = MLM[it], Mi = fmaxf(m, cm);
;                 bcum[lane] = bc; et[lane] = e; Ms[lane] = Mi; wint[lane] = __expf(m - Mi); nv[lane] = MLDN[(size_t)it * 64 + lane]; }
.LBB0_526:
	s_ashr_i32 s20, s81, 10
	s_ashr_i32 s21, s20, 31
	s_bfe_u32 s85, s81, 0x20008
	s_and_b32 s87, s81, 0xff
	s_lshl_b64 s[4:5], s[20:21], 20
	v_readlane_b32 s2, v251, 8
	v_readlane_b32 s3, v251, 9
	s_add_u32 s22, s2, s4
	s_addc_u32 s23, s3, s5
	s_and_b32 s4, s81, 0xfffffc00
	s_lshl_b32 s24, s85, 8
	s_or_b32 s79, s24, s4
	s_or_b32 s26, s79, s87
	s_and_saveexec_b64 s[4:5], s[40:41]
	s_xor_b64 s[38:39], exec, s[4:5]
	s_ashr_i32 s27, s26, 31
	s_or_saveexec_b64 s[38:39], s[38:39]
	s_lshl_b32 s84, s87, 6
	v_or_b32_e32 v4, s84, v1
	v_mov_b64_e32 v[2:3], s[26:27]
	v_lshlrev_b32_e32 v18, 6, v4
	s_xor_b64 exec, exec, s[38:39]
	s_cbranch_execz .LBB0_530
	v_mov_b32_e32 v19, v0
	v_lshl_add_u64 v[2:3], s[22:23], 0, v[18:19]
	s_lshl_b32 s28, s85, 2
	v_lshl_add_u64 v[2:3], v[2:3], 0, s[28:29]
	global_load_dword v4, v[2:3], off offset:16
	s_nop 0
	global_load_dword v2, v[2:3], off
	s_mov_b32 s2, 0x3f317217
	s_ashr_i32 s27, s26, 31
	s_lshl_b64 s[4:5], s[26:27], 2
	s_waitcnt vmcnt(0)
	v_max_f32_e32 v3, v4, v4
	v_mul_f32_e64 v4, |v4|, s12
	v_exp_f32_e32 v4, v4
	v_min_f32_e32 v3, 0, v3
	v_add_f32_e32 v4, 1.0, v4
	v_cmp_gt_f32_e32 vcc, s1, v4
	s_nop 1
	v_cndmask_b32_e64 v5, 0, 32, vcc
	v_ldexp_f32 v4, v4, v5
	v_log_f32_e32 v4, v4
	s_nop 0
	v_mul_f32_e32 v5, 0x3f317217, v4
	v_fma_f32 v5, v4, s2, -v5
	v_fmac_f32_e32 v5, 0x3377d1cf, v4
	s_mov_b32 s2, 0x7f800000
	v_fmac_f32_e32 v5, 0x3f317217, v4
	v_cmp_lt_f32_e64 s[74:75], |v4|, s2
	v_readlane_b32 s2, v251, 16
	s_add_u32 s4, s2, s4
	v_cndmask_b32_e64 v4, v4, v5, s[74:75]
	v_cndmask_b32_e32 v5, 0, v244, vcc
	v_sub_f32_e32 v4, v4, v5
	v_sub_f32_e32 v3, v3, v4
	ds_bpermute_b32 v4, v61, v3
	v_readlane_b32 s2, v251, 17
	s_addc_u32 s5, s2, s5
	global_load_dword v110, v0, s[4:5]
	v_mov_b64_e32 v[136:137], s[26:27]
	v_lshlrev_b64 v[136:137], 8, v[136:137]
	v_lshl_add_u64 v[136:137], v[30:31], 0, v[136:137]
	global_load_dword v111, v[136:137], off
	s_waitcnt lgkmcnt(0)
	v_add_f32_e32 v4, v3, v4
	v_cndmask_b32_e64 v3, v4, v3, s[46:47]
	ds_bpermute_b32 v4, v62, v3
	s_waitcnt lgkmcnt(0)
	v_add_f32_e32 v4, v3, v4
	v_cndmask_b32_e64 v3, v4, v3, s[48:49]
	ds_bpermute_b32 v4, v63, v3
	s_waitcnt lgkmcnt(0)
	v_add_f32_e32 v4, v3, v4
	v_cndmask_b32_e64 v3, v4, v3, s[50:51]
	ds_bpermute_b32 v4, v64, v3
	s_waitcnt lgkmcnt(0)
	v_add_f32_e32 v4, v3, v4
	v_cndmask_b32_e64 v3, v4, v3, s[52:53]
	ds_bpermute_b32 v4, v65, v3
	s_waitcnt lgkmcnt(0)
	v_add_f32_e32 v4, v3, v4
	v_cndmask_b32_e64 v3, v4, v3, s[54:55]
	ds_bpermute_b32 v4, v66, v3
	s_waitcnt lgkmcnt(0)
	v_add_f32_e32 v4, v3, v4
	v_cndmask_b32_e64 v3, v4, v3, s[56:57]
	v_sub_f32_e32 v2, v2, v3
	ds_bpermute_b32 v4, v61, v2
	s_waitcnt lgkmcnt(0)
	v_max_f32_e32 v4, v4, v4
	v_max_f32_e32 v4, v2, v4
	v_cndmask_b32_e64 v4, v4, v2, s[46:47]
	ds_bpermute_b32 v5, v62, v4
	s_waitcnt lgkmcnt(0)
	v_max_f32_e32 v5, v5, v5
	v_max_f32_e32 v5, v4, v5
	v_cndmask_b32_e64 v4, v5, v4, s[48:49]
	ds_bpermute_b32 v5, v63, v4
	s_waitcnt lgkmcnt(0)
	v_max_f32_e32 v5, v5, v5
	v_max_f32_e32 v5, v4, v5
	v_cndmask_b32_e64 v4, v5, v4, s[50:51]
	ds_bpermute_b32 v5, v64, v4
	s_waitcnt lgkmcnt(0)
	v_max_f32_e32 v5, v5, v5
	v_max_f32_e32 v5, v4, v5
	v_cndmask_b32_e64 v4, v5, v4, s[52:53]
	ds_bpermute_b32 v5, v65, v4
	s_waitcnt lgkmcnt(0)
	v_max_f32_e32 v5, v5, v5
	v_max_f32_e32 v5, v4, v5
	v_cndmask_b32_e64 v4, v5, v4, s[54:55]
	ds_bpermute_b32 v5, v66, v4
	v_max_f32_e32 v6, v4, v4
	s_waitcnt lgkmcnt(0)
	v_max_f32_e32 v5, v5, v5
	v_max_f32_e32 v5, v6, v5
	v_cndmask_b32_e64 v4, v5, v4, s[56:57]
	v_max_f32_e32 v4, v4, v4
	s_lshl_b64 s[4:5], s[26:27], 8
	s_waitcnt vmcnt(0)
	v_mov_b32_e32 v5, v110
	v_max_f32_e32 v6, v5, v5
	v_max_f32_e32 v4, v6, v4
	ds_write_b32 v55, v3
	ds_write_b32 v56, v2
	ds_write_b32 v57, v4
	v_sub_f32_e32 v2, v5, v4
	v_mul_f32_e32 v2, 0x3fb8aa3b, v2
	v_exp_f32_e32 v2, v2
	ds_write_b32 v58, v2
	v_lshl_add_u64 v[2:3], v[30:31], 0, s[4:5]
	v_mov_b32_e32 v2, v111
	s_waitcnt vmcnt(0)
	ds_write_b32 v59, v2
	v_mov_b64_e32 v[2:3], s[26:27]

; __device__ __forceinline__ bf16_t f2bf(float f) { return (bf16_t)(cvt_pk_bf16(f, 0.f) & 0xffffu); }
; __device__ __forceinline__ float row16_sum(float x) { x += dppf<0xB1>(x); x += dppf<0x4E>(x); x += dppf<0x141>(x); x += dppf<0x140>(x); return x; }
; __device__ __forceinline__ f32x4 mma16(bf16x8 a, bf16x8 b, f32x4 c) { return __builtin_amdgcn_mfma_f32_16x16x32_bf16(a, b, c, 0, 0, 0); }
; __device__ __forceinline__ void ml_out(LAS unsigned char* L, const bf16_t* Z, const float* GATES, const bf16_t* MLC, const float* MLDN, const float* MLM, const float* gain, bf16_t* Y) {
;     ...
;                 for (int r = 0; r < 4; ++r) { const int i = ti * 16 + 4 * fq + r; const float Mi = Ms[i]; float rsum = 0.f;
; #pragma unroll
;                     for (int u = 0; u < 2; ++u) { const int s = (ts0 + u) * 16 + fr; const float val = (s <= i) ? acc[u][r] * __expf(et[s] - Mi) : 0.f; Sm[i * 72 + s] = f2bf(val); rsum += val; }
;                     rsum = row16_sum(rsum); if (fr == 0) denp[i * 2 + (wid & 1)] = rsum; } }
;             __syncthreads();
;             { const int ti = wid >> 1, tv0 = (wid & 1) * 4; f32x4 acc[4];
; #pragma unroll
;                 for (int u = 0; u < 4; ++u) acc[u] = (f32x4){0.f, 0.f, 0.f, 0.f};
; #pragma unroll
;                 for (int kk = 0; kk < 2; ++kk) { const bf16x8 av = lfrag(Sm, 72, ti * 16 + fr, kk * 32 + 8 * fq);
; #pragma unroll
;                     for (int u = 0; u < 4; ++u) acc[u] = mma16(av, lfrag(Vt, 72, (tv0 + u) * 16 + fr, kk * 32 + 8 * fq), acc[u]); }
; #pragma unroll
;                 for (int kk = 0; kk < 2; ++kk) { const bf16x8 av = lfrag(Qw, 72, ti * 16 + fr, kk * 32 + 8 * fq);
; #pragma unroll
;                     for (int u = 0; u < 4; ++u) acc[u] = mma16(av, lfrag(Cs, 72, (tv0 + u) * 16 + fr, kk * 32 + 8 * fq), acc[u]); }
; #pragma unroll
;                 for (int r = 0; r < 4; ++r) { const int i = ti * 16 + 4 * fq + r; const float den = denp[2 * i] + denp[2 * i + 1] + deni[i];
;                     const float dd = fmaxf(fabsf(den), __expf(-(bcum[i] + Ms[i]))), inv = 1.f / dd; const int tl = g ? 63 - i : i;
; #pragma unroll
;                     for (int u = 0; u < 4; ++u) { const int v = (tv0 + u) * 16 + fr; const float hv = acc[u][r] * inv; if (g == 0) Hacc[tl * 132 + v] = hv; else Hacc[tl * 132 + v] += hv; } } }
;             __syncthreads();
.LBB0_554:
	s_or_b64 exec, exec, s[24:25]
	v_add_f32_e32 v3, 0, v3
	s_waitcnt lgkmcnt(1)
	v_cvt_pk_bf16_f32 v4, v2, s0
	v_add_f32_e32 v2, v3, v2
	v_add_u32_e32 v43, v54, v79
	ds_write_b16 v78, v4 offset:55328
	v_add_f32_dpp v2, v2, v2 quad_perm:[1,0,3,2] row_mask:0xf bank_mask:0xf bound_ctrl:1
	s_nop 1
	v_add_f32_dpp v2, v2, v2 quad_perm:[2,3,0,1] row_mask:0xf bank_mask:0xf bound_ctrl:1
	s_nop 1
	v_add_f32_dpp v2, v2, v2 row_half_mirror row_mask:0xf bank_mask:0xf bound_ctrl:1
	s_nop 1
	v_mov_b32_dpp v3, v2 row_mirror row_mask:0xf bank_mask:0xf bound_ctrl:1
	s_and_saveexec_b64 s[24:25], s[44:45]
	v_add_f32_e32 v2, v2, v3
	ds_write_b32 v43, v2
	s_or_b64 exec, exec, s[24:25]
	s_waitcnt lgkmcnt(0)
	s_barrier
	ds_read_b128 v[2:5], v38 offset:55296
	ds_read_b128 v[6:9], v101 offset:18432
	ds_read_b128 v[10:13], v101 offset:20736
	ds_read_b128 v[14:17], v101 offset:23040
	ds_read_b128 v[102:105], v101 offset:25344
	s_waitcnt lgkmcnt(3)
	v_mfma_f32_16x16x32_bf16 v[6:9], v[2:5], v[6:9], 0
	v_readlane_b32 s2, v253, 2
	s_waitcnt lgkmcnt(2)
	v_mfma_f32_16x16x32_bf16 v[10:13], v[2:5], v[10:13], 0
	v_add_u32_e32 v44, s2, v70
	s_waitcnt lgkmcnt(1)
	v_mfma_f32_16x16x32_bf16 v[14:17], v[2:5], v[14:17], 0
	s_waitcnt lgkmcnt(0)
	v_mfma_f32_16x16x32_bf16 v[2:5], v[2:5], v[102:105], 0
	ds_read_b128 v[102:105], v38 offset:55360
	ds_read_b128 v[106:109], v101 offset:18496
	s_waitcnt lgkmcnt(0)
	v_mfma_f32_16x16x32_bf16 v[6:9], v[102:105], v[106:109], v[6:9]
	ds_read_b128 v[106:109], v101 offset:20800
	s_waitcnt lgkmcnt(0)
	v_mfma_f32_16x16x32_bf16 v[10:13], v[102:105], v[106:109], v[10:13]
	ds_read_b128 v[106:109], v101 offset:23104
	s_waitcnt lgkmcnt(0)
	v_mfma_f32_16x16x32_bf16 v[14:17], v[102:105], v[106:109], v[14:17]
	ds_read_b128 v[106:109], v101 offset:25408
	s_waitcnt lgkmcnt(0)
	v_mfma_f32_16x16x32_bf16 v[2:5], v[102:105], v[106:109], v[2:5]
	ds_read_b128 v[102:105], v38 offset:64512
	ds_read_b128 v[106:109], v101 offset:36864
	s_waitcnt lgkmcnt(0)
	v_mfma_f32_16x16x32_bf16 v[6:9], v[102:105], v[106:109], v[6:9]
	ds_read_b128 v[106:109], v101 offset:39168
	s_waitcnt lgkmcnt(0)
	v_mfma_f32_16x16x32_bf16 v[10:13], v[102:105], v[106:109], v[10:13]
	ds_read_b128 v[106:109], v101 offset:41472
	s_waitcnt lgkmcnt(0)
	v_mfma_f32_16x16x32_bf16 v[14:17], v[102:105], v[106:109], v[14:17]
	ds_read_b128 v[106:109], v101 offset:43776
	s_waitcnt lgkmcnt(0)
	v_mfma_f32_16x16x32_bf16 v[102:105], v[102:105], v[106:109], v[2:5]
	ds_read_b128 v[106:109], v38 offset:64576
	s_nop 1
	ds_read_b128 v[2:5], v101 offset:36928
	ds_read_b64 v[20:21], v44
	s_waitcnt lgkmcnt(0)
	v_add_f32_e32 v19, v20, v21
	v_mfma_f32_16x16x32_bf16 v[2:5], v[106:109], v[2:5], v[6:9]
	ds_read_b32 v20, v80
	s_waitcnt lgkmcnt(0)
	v_add_f32_e32 v19, v19, v20
	ds_read_b128 v[6:9], v101 offset:39232
	s_waitcnt lgkmcnt(0)
	v_mfma_f32_16x16x32_bf16 v[6:9], v[106:109], v[6:9], v[10:13]
	s_nop 2
	ds_read_b128 v[10:13], v101 offset:41536
	s_waitcnt lgkmcnt(0)
	v_mfma_f32_16x16x32_bf16 v[10:13], v[106:109], v[10:13], v[14:17]
	s_nop 2
	ds_read_b128 v[14:17], v101 offset:43840
	ds_read_b32 v20, v81
	ds_read_b32 v21, v39
	s_waitcnt lgkmcnt(2)
	v_mfma_f32_16x16x32_bf16 v[14:17], v[106:109], v[14:17], v[102:105]
	s_waitcnt lgkmcnt(0)
	v_add_f32_e32 v20, v20, v21
	v_mul_f32_e32 v20, 0xbfb8aa3b, v20
	v_exp_f32_e32 v20, v20
	s_nop 0
	v_max_f32_e64 v19, |v19|, v20
	v_div_scale_f32 v20, s[4:5], v19, v19, 1.0
	v_rcp_f32_e32 v21, v20
	s_nop 0
	v_fma_f32 v41, -v20, v21, 1.0
	v_fmac_f32_e32 v21, v41, v21
	v_div_scale_f32 v41, vcc, 1.0, v19, 1.0
	v_mul_f32_e32 v45, v41, v21
	v_fma_f32 v102, -v20, v45, v41
	v_fmac_f32_e32 v45, v102, v21
	v_fma_f32 v20, -v20, v45, v41
	v_div_fmas_f32 v20, v20, v21, v45
	v_div_fixup_f32 v19, v20, v19, 1.0
	v_mul_f32_e32 v2, v2, v19
	v_mul_f32_e32 v6, v6, v19
	ds_write2_b32 v82, v2, v6 offset1:16
	v_mul_f32_e32 v2, v10, v19
	v_mul_f32_e32 v6, v14, v19
	ds_write2_b32 v82, v2, v6 offset0:32 offset1:48
	ds_read_b32 v2, v71
	ds_read_b32 v6, v83
	ds_read_b32 v10, v84
	v_add_u32_e32 v21, s2, v73
	ds_read_b64 v[102:103], v21
	s_waitcnt lgkmcnt(2)
	v_add_f32_e32 v2, v2, v6
	v_mul_f32_e32 v2, 0xbfb8aa3b, v2
	v_exp_f32_e32 v2, v2
	s_waitcnt lgkmcnt(0)
	v_add_f32_e32 v14, v102, v103
	v_add_f32_e32 v10, v10, v14
	v_max_f32_e64 v2, |v10|, v2
	v_div_scale_f32 v6, s[4:5], v2, v2, 1.0
	v_rcp_f32_e32 v10, v6
	s_nop 0
	v_fma_f32 v14, -v6, v10, 1.0
	v_fmac_f32_e32 v10, v14, v10
	v_div_scale_f32 v14, vcc, 1.0, v2, 1.0
	v_mul_f32_e32 v19, v14, v10
	v_fma_f32 v20, -v6, v19, v14
	v_fmac_f32_e32 v19, v20, v10
	v_fma_f32 v6, -v6, v19, v14
	v_div_fmas_f32 v6, v6, v10, v19
	v_div_fixup_f32 v2, v6, v2, 1.0
	v_mul_f32_e32 v3, v3, v2
	v_mul_f32_e32 v6, v7, v2
	ds_write2_b32 v85, v3, v6 offset1:16
	v_mul_f32_e32 v3, v11, v2
	v_mul_f32_e32 v2, v15, v2
	ds_write2_b32 v85, v3, v2 offset0:32 offset1:48
	v_add_u32_e32 v20, s2, v76
	ds_read_b32 v6, v74
	ds_read_b32 v7, v86
	ds_read_b32 v10, v87
	ds_read_b64 v[2:3], v20
	v_add_u32_e32 v19, s2, v79
	s_waitcnt lgkmcnt(0)
	v_add_f32_e32 v2, v2, v3
	v_add_f32_e32 v3, v6, v7
	v_mul_f32_e32 v3, 0xbfb8aa3b, v3
	v_exp_f32_e32 v3, v3
	v_add_f32_e32 v2, v10, v2
	v_max_f32_e64 v2, |v2|, v3
	v_div_scale_f32 v3, s[4:5], v2, v2, 1.0
	v_rcp_f32_e32 v6, v3
	s_nop 0
	v_fma_f32 v7, -v3, v6, 1.0
	v_fmac_f32_e32 v6, v7, v6
	v_div_scale_f32 v7, vcc, 1.0, v2, 1.0
	v_mul_f32_e32 v10, v7, v6
	v_fma_f32 v11, -v3, v10, v7
	v_fmac_f32_e32 v10, v11, v6
	v_fma_f32 v3, -v3, v10, v7
	v_div_fmas_f32 v3, v3, v6, v10
	v_div_fixup_f32 v2, v3, v2, 1.0
	v_mul_f32_e32 v3, v4, v2
	v_mul_f32_e32 v4, v8, v2
	ds_write2_b32 v88, v3, v4 offset1:16
	v_mul_f32_e32 v3, v12, v2
	v_mul_f32_e32 v2, v16, v2
	ds_write2_b32 v88, v3, v2 offset0:32 offset1:48
	ds_read_b32 v4, v77
	ds_read_b32 v6, v89
	ds_read_b32 v7, v90
	ds_read_b64 v[2:3], v19
	s_waitcnt lgkmcnt(0)
	v_add_f32_e32 v2, v2, v3
	v_add_f32_e32 v3, v4, v6
	v_mul_f32_e32 v3, 0xbfb8aa3b, v3
	v_exp_f32_e32 v3, v3
	v_add_f32_e32 v2, v7, v2
	v_max_f32_e64 v2, |v2|, v3
	v_div_scale_f32 v3, s[4:5], v2, v2, 1.0
	v_rcp_f32_e32 v4, v3
	s_add_i32 s4, s79, s87
	s_addk_i32 s4, 0x800
	s_xor_b32 s24, s4, 0xff
	v_fma_f32 v6, -v3, v4, 1.0
	v_fmac_f32_e32 v4, v6, v4
	v_div_scale_f32 v6, vcc, 1.0, v2, 1.0
	v_mul_f32_e32 v7, v6, v4
	v_fma_f32 v8, -v3, v7, v6
	v_fmac_f32_e32 v7, v8, v4
	v_fma_f32 v3, -v3, v7, v6
	v_div_fmas_f32 v3, v3, v4, v7
	v_div_fixup_f32 v2, v3, v2, 1.0
	v_mul_f32_e32 v3, v5, v2
	v_mul_f32_e32 v4, v9, v2
	ds_write2_b32 v91, v3, v4 offset1:16
	v_mul_f32_e32 v3, v13, v2
	v_mul_f32_e32 v2, v17, v2
	ds_write2_b32 v91, v3, v2 offset0:32 offset1:48
	s_waitcnt lgkmcnt(0)
	s_barrier
; __device__ __forceinline__ float logsig(float x) { return fminf(x, 0.f) - __logf(1.f + __expf(-fabsf(x))); }
; __device__ __forceinline__ void ml_out(LAS unsigned char* L, const bf16_t* Z, const float* GATES, const bf16_t* MLC, const float* MLDN, const float* MLM, const float* gain, bf16_t* Y) {
;     ...
;             const int j = g ? 255 - c : c, chain = g * 8 + b * 4 + h, it = chain * 256 + j;
;             if (wid == 0) { const int t = g ? (64 * c + 63 - lane) : (64 * c + lane); const size_t row = (size_t)b * S_ + t;
;                 const float fpre = GATES[row * 16 + g * 8 + 4 + h], ipre = GATES[row * 16 + g * 8 + h];
;                 float bc = logsig(fpre);
;                 for (int o = 1; o < 64; o <<= 1) { const float v = __shfl_up(bc, o); if (lane >= o) bc += v; }
;                 const float e = ipre - bc; float cm = e;
;                 for (int o = 1; o < 64; o <<= 1) { const float v = __shfl_up(cm, o); if (lane >= o) cm = fmaxf(cm, v); }
;                 const float m = MLM[it], Mi = fmaxf(m, cm);
;                 bcum[lane] = bc; et[lane] = e; Ms[lane] = Mi; wint[lane] = __expf(m - Mi); nv[lane] = MLDN[(size_t)it * 64 + lane]; }
	s_and_saveexec_b64 s[4:5], s[40:41]
	s_xor_b64 s[26:27], exec, s[4:5]
	s_ashr_i32 s25, s24, 31
	s_or_saveexec_b64 s[26:27], s[26:27]
	v_mov_b64_e32 v[2:3], s[24:25]
	s_xor_b64 exec, exec, s[26:27]
	s_cbranch_execz .LBB0_560
	v_xor_b32_e32 v2, 0xfc0, v18
	v_mov_b32_e32 v3, v0
	v_lshl_add_u64 v[2:3], s[22:23], 0, v[2:3]
	s_lshl_b32 s4, s85, 2
	s_mov_b32 s5, s29
	v_lshl_add_u64 v[2:3], v[2:3], 0, s[4:5]
	global_load_dword v4, v[2:3], off offset:48
	s_nop 0
	global_load_dword v2, v[2:3], off offset:32
	s_mov_b32 s2, 0x3f317217
	s_ashr_i32 s25, s24, 31
	s_lshl_b64 s[4:5], s[24:25], 2
	s_waitcnt vmcnt(1)
	v_max_f32_e32 v3, v4, v4
	v_mul_f32_e64 v4, |v4|, s12
	v_exp_f32_e32 v4, v4
	v_min_f32_e32 v3, 0, v3
	v_add_f32_e32 v4, 1.0, v4
	v_cmp_gt_f32_e32 vcc, s1, v4
	s_nop 1
	v_cndmask_b32_e64 v5, 0, 32, vcc
	v_ldexp_f32 v4, v4, v5
	v_log_f32_e32 v4, v4
	s_nop 0
	v_mul_f32_e32 v5, 0x3f317217, v4
	v_fma_f32 v5, v4, s2, -v5
	v_fmac_f32_e32 v5, 0x3377d1cf, v4
	s_mov_b32 s2, 0x7f800000
	v_fmac_f32_e32 v5, 0x3f317217, v4
	v_cmp_lt_f32_e64 s[74:75], |v4|, s2
	v_readlane_b32 s2, v251, 16
	s_add_u32 s4, s2, s4
	v_cndmask_b32_e64 v4, v4, v5, s[74:75]
	v_cndmask_b32_e32 v5, 0, v244, vcc
	v_sub_f32_e32 v4, v4, v5
	v_sub_f32_e32 v3, v3, v4
	ds_bpermute_b32 v4, v61, v3
	v_readlane_b32 s2, v251, 17
	s_addc_u32 s5, s2, s5
	global_load_dword v110, v0, s[4:5]
	v_mov_b64_e32 v[136:137], s[24:25]
	v_lshlrev_b64 v[136:137], 8, v[136:137]
	v_lshl_add_u64 v[136:137], v[30:31], 0, v[136:137]
	global_load_dword v111, v[136:137], off
	s_waitcnt lgkmcnt(0)
	v_add_f32_e32 v4, v3, v4
	v_cndmask_b32_e64 v3, v4, v3, s[46:47]
	ds_bpermute_b32 v4, v62, v3
	s_waitcnt lgkmcnt(0)
	v_add_f32_e32 v4, v3, v4
	v_cndmask_b32_e64 v3, v4, v3, s[48:49]
	ds_bpermute_b32 v4, v63, v3
	s_waitcnt lgkmcnt(0)
	v_add_f32_e32 v4, v3, v4
	v_cndmask_b32_e64 v3, v4, v3, s[50:51]
	ds_bpermute_b32 v4, v64, v3
	s_waitcnt lgkmcnt(0)
	v_add_f32_e32 v4, v3, v4
	v_cndmask_b32_e64 v3, v4, v3, s[52:53]
	ds_bpermute_b32 v4, v65, v3
	s_waitcnt lgkmcnt(0)
	v_add_f32_e32 v4, v3, v4
	v_cndmask_b32_e64 v3, v4, v3, s[54:55]
	ds_bpermute_b32 v4, v66, v3
	s_waitcnt lgkmcnt(0)
	v_add_f32_e32 v4, v3, v4
	v_cndmask_b32_e64 v3, v4, v3, s[56:57]
	s_waitcnt vmcnt(0)
	v_sub_f32_e32 v2, v2, v3
	ds_bpermute_b32 v4, v61, v2
	s_waitcnt lgkmcnt(0)
	v_max_f32_e32 v4, v4, v4
	v_max_f32_e32 v4, v2, v4
	v_cndmask_b32_e64 v4, v4, v2, s[46:47]
	ds_bpermute_b32 v5, v62, v4
	s_waitcnt lgkmcnt(0)
	v_max_f32_e32 v5, v5, v5
	v_max_f32_e32 v5, v4, v5
	v_cndmask_b32_e64 v4, v5, v4, s[48:49]
	ds_bpermute_b32 v5, v63, v4
	s_waitcnt lgkmcnt(0)
	v_max_f32_e32 v5, v5, v5
	v_max_f32_e32 v5, v4, v5
	v_cndmask_b32_e64 v4, v5, v4, s[50:51]
	ds_bpermute_b32 v5, v64, v4
	s_waitcnt lgkmcnt(0)
	v_max_f32_e32 v5, v5, v5
	v_max_f32_e32 v5, v4, v5
	v_cndmask_b32_e64 v4, v5, v4, s[52:53]
	ds_bpermute_b32 v5, v65, v4
	s_waitcnt lgkmcnt(0)
	v_max_f32_e32 v5, v5, v5
	v_max_f32_e32 v5, v4, v5
	v_cndmask_b32_e64 v4, v5, v4, s[54:55]
	ds_bpermute_b32 v5, v66, v4
	v_max_f32_e32 v6, v4, v4
	s_waitcnt lgkmcnt(0)
	v_max_f32_e32 v5, v5, v5
	v_max_f32_e32 v5, v6, v5
	v_cndmask_b32_e64 v4, v5, v4, s[56:57]
	v_max_f32_e32 v4, v4, v4
	s_lshl_b64 s[4:5], s[24:25], 8
	s_waitcnt vmcnt(0)
	v_mov_b32_e32 v5, v110
	v_max_f32_e32 v6, v5, v5
	v_max_f32_e32 v4, v6, v4
	ds_write_b32 v55, v3
	ds_write_b32 v56, v2
	ds_write_b32 v57, v4
	v_sub_f32_e32 v2, v5, v4
	v_mul_f32_e32 v2, 0x3fb8aa3b, v2
	v_exp_f32_e32 v2, v2
	ds_write_b32 v58, v2
	v_lshl_add_u64 v[2:3], v[30:31], 0, s[4:5]
	v_mov_b32_e32 v2, v111
	s_waitcnt vmcnt(0)
	ds_write_b32 v59, v2
	v_mov_b64_e32 v[2:3], s[24:25]

; __device__ __forceinline__ int obid() { int b = __builtin_amdgcn_workgroup_id_x(); asm volatile("" : "+s"(b)); return b; }
; __device__ __forceinline__ unsigned cvt_pk_bf16(float lo, float hi) { const f32x2_t v = {lo, hi}; const bf16x2_t b = __builtin_convertvector(v, bf16x2_t); return __builtin_bit_cast(unsigned, b); }
; __device__ __forceinline__ float wave_sum(float x) { for (int o = 32; o >= 1; o >>= 1) x += __shfl_xor(x, o); return x; }
; __device__ __forceinline__ void p0_rows(const float* x, float* X, bf16_t* XB, float* SS) {
;     ...
;     for (int row = obid() * 8 + wid; row < T_; row += gridDim.x * 8) {
;         const float* xr = x + (size_t)row * 1024; float ss = 0.f;
; #pragma unroll
;         for (int i = 0; i < 4; ++i) { const int col = i * 256 + lane * 4; const f32x4 v = *(const f32x4*)(xr + col); *(f32x4*)(X + (size_t)row * 1024 + col) = v;
;             u32x2 w; w.x = cvt_pk_bf16(v[0], v[1]); w.y = cvt_pk_bf16(v[2], v[3]); *(u32x2*)(XB + (size_t)row * 1024 + col) = w;
;             ss += (v[0] * v[0] + v[1] * v[1]) + (v[2] * v[2] + v[3] * v[3]); }
;         ss = wave_sum(ss);
;         if (lane < 16) SS[(size_t)row * 16 + lane] = lane == 0 ? ss : 0.f;
.LBB0_784:
	v_ashrrev_i32_e32 v3, 31, v2
	v_lshlrev_b64 v[22:23], 12, v[2:3]
	v_lshl_add_u64 v[24:25], v[6:7], 0, v[22:23]
	s_waitcnt lgkmcnt(0)
	global_load_dwordx4 v[18:21], v[24:25], off
	global_load_dwordx4 v[30:33], v[24:25], off offset:1024
	global_load_dwordx4 v[34:37], v[24:25], off offset:2048
	global_load_dwordx4 v[38:41], v[24:25], off offset:3072
	v_lshl_add_u64 v[22:23], v[8:9], 0, v[22:23]
	v_lshlrev_b64 v[28:29], 11, v[2:3]
	v_lshl_add_u64 v[28:29], v[10:11], 0, v[28:29]
	s_waitcnt vmcnt(3)
	v_mul_f32_e32 v17, v19, v19
	global_store_dwordx4 v[22:23], v[18:21], off
	v_cvt_pk_bf16_f32 v26, v18, v19
	v_cvt_pk_bf16_f32 v27, v20, v21
	v_fmac_f32_e32 v17, v18, v18
	v_mul_f32_e32 v18, v21, v21
	global_store_dwordx2 v[28:29], v[26:27], off
	v_fmac_f32_e32 v18, v20, v20
	v_add_f32_e32 v17, v17, v18
	s_waitcnt vmcnt(4)
	v_mov_b32_e32 v18, v30
	v_mov_b32_e32 v19, v31
	v_mov_b32_e32 v20, v32
	v_mov_b32_e32 v21, v33
	v_cvt_pk_bf16_f32 v26, v18, v19
	global_store_dwordx4 v[22:23], v[18:21], off offset:1024
	v_cvt_pk_bf16_f32 v27, v20, v21
	global_store_dwordx2 v[28:29], v[26:27], off offset:512
	v_mul_f32_e32 v19, v19, v19
	v_fmac_f32_e32 v19, v18, v18
	v_mul_f32_e32 v18, v21, v21
	v_fmac_f32_e32 v18, v20, v20
	v_add_f32_e32 v18, v19, v18
	v_add_f32_e32 v17, v17, v18
	s_waitcnt vmcnt(5)
	v_mov_b32_e32 v18, v34
	v_mov_b32_e32 v19, v35
	v_mov_b32_e32 v20, v36
	v_mov_b32_e32 v21, v37
	v_cvt_pk_bf16_f32 v26, v18, v19
	global_store_dwordx4 v[22:23], v[18:21], off offset:2048
	v_cvt_pk_bf16_f32 v27, v20, v21
	global_store_dwordx2 v[28:29], v[26:27], off offset:1024
	v_mul_f32_e32 v19, v19, v19
	v_fmac_f32_e32 v19, v18, v18
	v_mul_f32_e32 v18, v21, v21
	v_fmac_f32_e32 v18, v20, v20
	v_add_f32_e32 v18, v19, v18
	v_add_f32_e32 v17, v17, v18
	s_waitcnt vmcnt(6)
	v_mov_b32_e32 v18, v38
	v_mov_b32_e32 v19, v39
	v_mov_b32_e32 v20, v40
	v_mov_b32_e32 v21, v41
	global_store_dwordx4 v[22:23], v[18:21], off offset:3072
	v_cvt_pk_bf16_f32 v22, v18, v19
	s_nop 0
	v_mul_f32_e32 v19, v19, v19
	v_fmac_f32_e32 v19, v18, v18
	v_mul_f32_e32 v18, v21, v21
	v_fmac_f32_e32 v18, v20, v20
	v_add_f32_e32 v18, v19, v18
	v_add_f32_e32 v17, v17, v18
	ds_bpermute_b32 v18, v1, v17
	v_cvt_pk_bf16_f32 v23, v20, v21
	global_store_dwordx2 v[28:29], v[22:23], off offset:1536
	s_waitcnt lgkmcnt(0)
	v_add_f32_e32 v17, v17, v18
	ds_bpermute_b32 v18, v12, v17
	s_waitcnt lgkmcnt(0)
	v_add_f32_e32 v17, v17, v18
	ds_bpermute_b32 v18, v13, v17
	s_waitcnt lgkmcnt(0)
	v_add_f32_e32 v17, v17, v18
	ds_bpermute_b32 v18, v14, v17
	s_waitcnt lgkmcnt(0)
	v_add_f32_e32 v17, v17, v18
	ds_bpermute_b32 v18, v15, v17
	s_waitcnt lgkmcnt(0)
	v_add_f32_e32 v17, v17, v18
	ds_bpermute_b32 v18, v16, v17
	s_and_saveexec_b64 s[24:25], vcc
	s_cbranch_execz .LBB0_783
	s_waitcnt lgkmcnt(0)
	v_add_f32_e32 v17, v17, v18
	v_lshlrev_b64 v[18:19], 6, v[2:3]
	v_cndmask_b32_e64 v17, 0, v17, s[40:41]
	v_lshl_add_u64 v[18:19], v[4:5], 0, v[18:19]
	global_store_dword v[18:19], v17, off
	s_branch .LBB0_783
